# A/B: barrier-time next-phase weight prefetch removed from the six barrier hooks
# speedup vs baseline: 1.0130x; 1.0130x over previous
; #define SEAM(k) do { if (IN(k) && IN((k) + 1)) { if (hi > 4096) cg::this_grid().sync(); else xcd_barrier(bar); } } while (0)
; __device__ __forceinline__ void xcd_barrier(const XcdBarrier& b) {
;     asm volatile("s_waitcnt vmcnt(0)" ::: "memory");
;     __syncthreads();
; __global__ void __launch_bounds__(NTHREADS, 2) mk_fwd(Args args) {
;     ...
;     SEAM(0);
.LBB0_132:
	s_or_b64 exec, exec, s[4:5]
	s_cmpk_lg_u32 s3, 0x100
	s_cbranch_scc1 .Lcv_skip_0
	v_readfirstlane_b32 vcc_lo, v204
	s_nop 3
	s_lshr_b32 vcc_lo, vcc_lo, 6
	s_cmp_eq_u32 vcc_lo, 0
	s_cbranch_scc1 .Lcv_skip_0
.Lcv_pfwait_0:
	s_waitcnt vmcnt(0)

; __device__ __forceinline__ unsigned cvt_pk_bf16(float lo, float hi) { unsigned r; asm volatile("v_cvt_pk_bf16_f32 %0, %1, %2" : "=v"(r) : "v"(lo), "v"(hi)); return r; }
; __device__ __forceinline__ void st16_wt(void* p, u32x4 v) { asm volatile("global_store_dwordx4 %0, %1, off sc1\n\ts_nop 1" :: "v"(p), "v"(v) : "memory"); }
; #define SEAM(k) do { if (IN(k) && IN((k) + 1)) { if (hi > 4096) cg::this_grid().sync(); else xcd_barrier(bar); } } while (0)
; __device__ __forceinline__ void tr_item(const float* __restrict__ W, int K, int N, bf16_t* WT, const float* __restrict__ kscale, int rowmode, int item, int lane) {
;     const int nblk = N >> 5, kb = item / nblk, nb = item - kb * nblk;
;     const int c = lane >> 3, q = lane & 7, k0 = kb * 64 + c * 8, n0 = nb * 32 + q * 4;
;     f32x4 v[8];
; #pragma unroll
;     for (int i = 0; i < 8; ++i) v[i] = __builtin_nontemporal_load((const f32x4*)(W + (size_t)(k0 + i) * N + n0));
;     if (kscale) { const f32x4 s0 = *(const f32x4*)(kscale + k0), s1 = *(const f32x4*)(kscale + k0 + 4);
; #pragma unroll
;         for (int i = 0; i < 4; ++i) { v[i] = v[i] * s0[i]; v[4 + i] = v[4 + i] * s1[i]; } }
;     int drow;
;     if (rowmode == 0) drow = n0;
;     else if (rowmode == 3) { const int g = n0 - pg8::C_GA; drow = g < 0 ? n0 : pg8::C_GA + (((g & 2047) >> 7) << 8) + ((g >> 11) << 7) + (g & 127); }
;     else drow = ((n0 >> 7) << 8) + (n0 & 127) + (rowmode == 2 ? 128 : 0);
; #pragma unroll
;     for (int e = 0; e < 4; ++e) { u32x4 o; o.x = cvt_pk_bf16(v[0][e], v[1][e]); o.y = cvt_pk_bf16(v[2][e], v[3][e]); o.z = cvt_pk_bf16(v[4][e], v[5][e]); o.w = cvt_pk_bf16(v[6][e], v[7][e]);
;         pg8::st16_wt(WT + (size_t)(drow + e) * K + k0, o); }
; __global__ void __launch_bounds__(NTHREADS, 2) mk_fwd(Args args) {
;     ...
;         SEAM(pb + 1);
.LBB0_400:
	s_or_b64 exec, exec, s[0:1]
	s_cmpk_lg_u32 s3, 0x100
	s_cbranch_scc1 .Lcv_skip_2
	v_readfirstlane_b32 vcc_lo, v204
	s_nop 3
	s_lshr_b32 vcc_lo, vcc_lo, 6
	s_cmp_eq_u32 vcc_lo, 0
	s_cbranch_scc1 .Lcv_skip_2
	s_cmp_lg_u32 s64, 0
	s_cbranch_scc1 .Lcv_pfwait_2
	v_and_b32_e32 v106, 63, v204
	v_lshrrev_b32_e32 v107, 3, v106
	v_and_b32_e32 v108, 7, v106
	v_readfirstlane_b32 vcc_lo, v204
	s_nop 3
	s_lshr_b32 vcc_lo, vcc_lo, 6
	s_mul_i32 vcc_hi, s85, 7
	s_add_i32 vcc_lo, vcc_lo, vcc_hi
	s_add_i32 vcc_lo, vcc_lo, -1
	s_add_i32 vcc_lo, vcc_lo, 1792
	s_cmp_ge_u32 vcc_lo, 3520
	s_cbranch_scc1 .Lcv_2_0_n0
	s_sub_u32 vcc_lo, vcc_lo, 0
	v_mov_b32_e32 v113, vcc_lo
	v_mul_u32_u24_e32 v109, 0x5d18, v113
	v_lshrrev_b32_e32 v109, 22, v109
	v_mul_u32_u24_e32 v110, 0xb0, v109
	v_sub_u32_e32 v110, v113, v110
	v_lshlrev_b32_e32 v109, 6, v109
	v_lshl_add_u32 v109, v107, 3, v109
	v_lshlrev_b32_e32 v110, 5, v110
	v_lshl_add_u32 v110, v108, 2, v110
	v_mul_u32_u24_e32 v111, 0x5800, v109
	v_lshl_add_u32 v111, v110, 2, v111
	v_lshrrev_b32_e32 v112, 7, v110
	v_lshlrev_b32_e32 v112, 8, v112
	v_and_b32_e32 v113, 0x7f, v110
	v_add_u32_e32 v112, v112, v113
	v_lshlrev_b32_e32 v112, 12, v112
	v_lshl_add_u32 v112, v109, 1, v112
	v_lshlrev_b32_e32 v113, 2, v109
	v_readlane_b32 vcc_lo, v250, 28
	v_readlane_b32 vcc_hi, v250, 29
	s_nop 4
	global_load_dwordx4 v[98:101], v113, vcc
	global_load_dwordx4 v[102:105], v113, vcc offset:16
	v_readlane_b32 vcc_lo, v250, 30
	v_readlane_b32 vcc_hi, v250, 31
	s_nop 4
	global_load_dwordx4 v[66:69], v111, vcc nt
	v_add_u32_e32 v111, 0x5800, v111
	global_load_dwordx4 v[70:73], v111, vcc nt
	v_add_u32_e32 v111, 0x5800, v111
	global_load_dwordx4 v[74:77], v111, vcc nt
	v_add_u32_e32 v111, 0x5800, v111
	global_load_dwordx4 v[78:81], v111, vcc nt
	v_add_u32_e32 v111, 0x5800, v111
	global_load_dwordx4 v[82:85], v111, vcc nt
	v_add_u32_e32 v111, 0x5800, v111
	global_load_dwordx4 v[86:89], v111, vcc nt
	v_add_u32_e32 v111, 0x5800, v111
	global_load_dwordx4 v[90:93], v111, vcc nt
	v_add_u32_e32 v111, 0x5800, v111
	global_load_dwordx4 v[94:97], v111, vcc nt
	v_readlane_b32 vcc_lo, v250, 36
	v_readlane_b32 vcc_hi, v250, 37
	s_nop 3
	s_add_u32 vcc_lo, vcc_lo, 0x5dc0000
	s_addc_u32 vcc_hi, vcc_hi, 0
	s_waitcnt vmcnt(0)
	v_mul_f32_e32 v66, v66, v98
	v_mul_f32_e32 v67, v67, v98
	v_mul_f32_e32 v68, v68, v98
	v_mul_f32_e32 v69, v69, v98
	v_mul_f32_e32 v70, v70, v99
	v_mul_f32_e32 v71, v71, v99
	v_mul_f32_e32 v72, v72, v99
	v_mul_f32_e32 v73, v73, v99
	v_mul_f32_e32 v74, v74, v100
	v_mul_f32_e32 v75, v75, v100
	v_mul_f32_e32 v76, v76, v100
	v_mul_f32_e32 v77, v77, v100
	v_mul_f32_e32 v78, v78, v101
	v_mul_f32_e32 v79, v79, v101
	v_mul_f32_e32 v80, v80, v101
	v_mul_f32_e32 v81, v81, v101
	v_mul_f32_e32 v82, v82, v102
	v_mul_f32_e32 v83, v83, v102
	v_mul_f32_e32 v84, v84, v102
	v_mul_f32_e32 v85, v85, v102
	v_mul_f32_e32 v86, v86, v103
	v_mul_f32_e32 v87, v87, v103
	v_mul_f32_e32 v88, v88, v103
	v_mul_f32_e32 v89, v89, v103
	v_mul_f32_e32 v90, v90, v104
	v_mul_f32_e32 v91, v91, v104
	v_mul_f32_e32 v92, v92, v104
	v_mul_f32_e32 v93, v93, v104
	v_mul_f32_e32 v94, v94, v105
	v_mul_f32_e32 v95, v95, v105
	v_mul_f32_e32 v96, v96, v105
	v_mul_f32_e32 v97, v97, v105
	v_cvt_pk_bf16_f32 v114, v66, v70
	v_cvt_pk_bf16_f32 v115, v74, v78
	v_cvt_pk_bf16_f32 v116, v82, v86
	v_cvt_pk_bf16_f32 v117, v90, v94
	v_cvt_pk_bf16_f32 v118, v67, v71
	v_cvt_pk_bf16_f32 v119, v75, v79
	v_cvt_pk_bf16_f32 v120, v83, v87
	v_cvt_pk_bf16_f32 v121, v91, v95
	v_cvt_pk_bf16_f32 v122, v68, v72
	v_cvt_pk_bf16_f32 v123, v76, v80
	v_cvt_pk_bf16_f32 v124, v84, v88
	v_cvt_pk_bf16_f32 v125, v92, v96
	v_cvt_pk_bf16_f32 v126, v69, v73
	v_cvt_pk_bf16_f32 v127, v77, v81
	v_cvt_pk_bf16_f32 v128, v85, v89
	v_cvt_pk_bf16_f32 v129, v93, v97
	global_store_dwordx4 v112, v[114:117], vcc sc1
	v_add_u32_e32 v112, 0x1000, v112
	global_store_dwordx4 v112, v[118:121], vcc sc1
	v_add_u32_e32 v112, 0x1000, v112
	global_store_dwordx4 v112, v[122:125], vcc sc1
	v_add_u32_e32 v112, 0x1000, v112
	global_store_dwordx4 v112, v[126:129], vcc sc1
	s_branch .Lcv_done_2_0

; __device__ __forceinline__ unsigned cvt_pk_bf16(float lo, float hi) { unsigned r; asm volatile("v_cvt_pk_bf16_f32 %0, %1, %2" : "=v"(r) : "v"(lo), "v"(hi)); return r; }
; __device__ __forceinline__ void st16_wt(void* p, u32x4 v) { asm volatile("global_store_dwordx4 %0, %1, off sc1\n\ts_nop 1" :: "v"(p), "v"(v) : "memory"); }
; #define SEAM(k) do { if (IN(k) && IN((k) + 1)) { if (hi > 4096) cg::this_grid().sync(); else xcd_barrier(bar); } } while (0)
; __device__ __forceinline__ void tr_item(const float* __restrict__ W, int K, int N, bf16_t* WT, const float* __restrict__ kscale, int rowmode, int item, int lane) {
;     const int nblk = N >> 5, kb = item / nblk, nb = item - kb * nblk;
;     const int c = lane >> 3, q = lane & 7, k0 = kb * 64 + c * 8, n0 = nb * 32 + q * 4;
;     f32x4 v[8];
; #pragma unroll
;     for (int i = 0; i < 8; ++i) v[i] = __builtin_nontemporal_load((const f32x4*)(W + (size_t)(k0 + i) * N + n0));
;     if (kscale) { const f32x4 s0 = *(const f32x4*)(kscale + k0), s1 = *(const f32x4*)(kscale + k0 + 4);
; #pragma unroll
;         for (int i = 0; i < 4; ++i) { v[i] = v[i] * s0[i]; v[4 + i] = v[4 + i] * s1[i]; } }
;     int drow;
;     if (rowmode == 0) drow = n0;
;     else if (rowmode == 3) { const int g = n0 - pg8::C_GA; drow = g < 0 ? n0 : pg8::C_GA + (((g & 2047) >> 7) << 8) + ((g >> 11) << 7) + (g & 127); }
;     else drow = ((n0 >> 7) << 8) + (n0 & 127) + (rowmode == 2 ? 128 : 0);
; #pragma unroll
;     for (int e = 0; e < 4; ++e) { u32x4 o; o.x = cvt_pk_bf16(v[0][e], v[1][e]); o.y = cvt_pk_bf16(v[2][e], v[3][e]); o.z = cvt_pk_bf16(v[4][e], v[5][e]); o.w = cvt_pk_bf16(v[6][e], v[7][e]);
;         pg8::st16_wt(WT + (size_t)(drow + e) * K + k0, o); }
; __global__ void __launch_bounds__(NTHREADS, 2) mk_fwd(Args args) {
;     ...
;         SEAM(pb + 2);
.LBB0_524:
	s_or_b64 exec, exec, s[0:1]
	s_cmpk_lg_u32 s3, 0x100
	s_cbranch_scc1 .Lcv_skip_3
	v_readfirstlane_b32 vcc_lo, v204
	s_nop 3
	s_lshr_b32 vcc_lo, vcc_lo, 6
	s_cmp_eq_u32 vcc_lo, 0
	s_cbranch_scc1 .Lcv_skip_3
	s_cmp_lg_u32 s64, 0
	s_cbranch_scc1 .Lcv_pfwait_3
	v_and_b32_e32 v106, 63, v204
	v_lshrrev_b32_e32 v107, 3, v106
	v_and_b32_e32 v108, 7, v106
	v_readfirstlane_b32 vcc_lo, v204
	s_nop 3
	s_lshr_b32 vcc_lo, vcc_lo, 6
	s_mul_i32 vcc_hi, s85, 7
	s_add_i32 vcc_lo, vcc_lo, vcc_hi
	s_add_i32 vcc_lo, vcc_lo, -1
	s_add_i32 vcc_lo, vcc_lo, 3584
	s_sub_u32 vcc_lo, vcc_lo, 3520
	v_mov_b32_e32 v113, vcc_lo
	v_mul_u32_u24_e32 v109, 0x5d18, v113
	v_lshrrev_b32_e32 v109, 22, v109
	v_mul_u32_u24_e32 v110, 0xb0, v109
	v_sub_u32_e32 v110, v113, v110
	v_lshlrev_b32_e32 v109, 6, v109
	v_lshl_add_u32 v109, v107, 3, v109
	v_lshlrev_b32_e32 v110, 5, v110
	v_lshl_add_u32 v110, v108, 2, v110
	v_mul_u32_u24_e32 v111, 0x5800, v109
	v_lshl_add_u32 v111, v110, 2, v111
	v_add_u32_e32 v111, 0x2c00000, v111
	v_lshrrev_b32_e32 v112, 7, v110
	v_lshlrev_b32_e32 v112, 8, v112
	v_and_b32_e32 v113, 0x7f, v110
	v_add_u32_e32 v112, v112, v113
	v_lshlrev_b32_e32 v112, 12, v112
	v_lshl_add_u32 v112, v109, 1, v112
	v_lshlrev_b32_e32 v113, 2, v109
	v_add_u32_e32 v113, 0x2000, v113
	v_readlane_b32 vcc_lo, v250, 28
	v_readlane_b32 vcc_hi, v250, 29
	s_nop 4
	global_load_dwordx4 v[98:101], v113, vcc
	global_load_dwordx4 v[102:105], v113, vcc offset:16
	v_readlane_b32 vcc_lo, v250, 30
	v_readlane_b32 vcc_hi, v250, 31
	s_nop 4
	global_load_dwordx4 v[66:69], v111, vcc nt
	v_add_u32_e32 v111, 0x5800, v111
	global_load_dwordx4 v[70:73], v111, vcc nt
	v_add_u32_e32 v111, 0x5800, v111
	global_load_dwordx4 v[74:77], v111, vcc nt
	v_add_u32_e32 v111, 0x5800, v111
	global_load_dwordx4 v[78:81], v111, vcc nt
	v_add_u32_e32 v111, 0x5800, v111
	global_load_dwordx4 v[82:85], v111, vcc nt
	v_add_u32_e32 v111, 0x5800, v111
	global_load_dwordx4 v[86:89], v111, vcc nt
	v_add_u32_e32 v111, 0x5800, v111
	global_load_dwordx4 v[90:93], v111, vcc nt
	v_add_u32_e32 v111, 0x5800, v111
	global_load_dwordx4 v[94:97], v111, vcc nt
	v_readlane_b32 vcc_lo, v250, 36
	v_readlane_b32 vcc_hi, v250, 37
	s_nop 3
	s_add_u32 vcc_lo, vcc_lo, 0x89c0000
	s_addc_u32 vcc_hi, vcc_hi, 0
	s_waitcnt vmcnt(0)
	v_mul_f32_e32 v66, v66, v98
	v_mul_f32_e32 v67, v67, v98
	v_mul_f32_e32 v68, v68, v98
	v_mul_f32_e32 v69, v69, v98
	v_mul_f32_e32 v70, v70, v99
	v_mul_f32_e32 v71, v71, v99
	v_mul_f32_e32 v72, v72, v99
	v_mul_f32_e32 v73, v73, v99
	v_mul_f32_e32 v74, v74, v100
	v_mul_f32_e32 v75, v75, v100
	v_mul_f32_e32 v76, v76, v100
	v_mul_f32_e32 v77, v77, v100
	v_mul_f32_e32 v78, v78, v101
	v_mul_f32_e32 v79, v79, v101
	v_mul_f32_e32 v80, v80, v101
	v_mul_f32_e32 v81, v81, v101
	v_mul_f32_e32 v82, v82, v102
	v_mul_f32_e32 v83, v83, v102
	v_mul_f32_e32 v84, v84, v102
	v_mul_f32_e32 v85, v85, v102
	v_mul_f32_e32 v86, v86, v103
	v_mul_f32_e32 v87, v87, v103
	v_mul_f32_e32 v88, v88, v103
	v_mul_f32_e32 v89, v89, v103
	v_mul_f32_e32 v90, v90, v104
	v_mul_f32_e32 v91, v91, v104
	v_mul_f32_e32 v92, v92, v104
	v_mul_f32_e32 v93, v93, v104
	v_mul_f32_e32 v94, v94, v105
	v_mul_f32_e32 v95, v95, v105
	v_mul_f32_e32 v96, v96, v105
	v_mul_f32_e32 v97, v97, v105
	v_cvt_pk_bf16_f32 v114, v66, v70
	v_cvt_pk_bf16_f32 v115, v74, v78
	v_cvt_pk_bf16_f32 v116, v82, v86
	v_cvt_pk_bf16_f32 v117, v90, v94
	v_cvt_pk_bf16_f32 v118, v67, v71
	v_cvt_pk_bf16_f32 v119, v75, v79
	v_cvt_pk_bf16_f32 v120, v83, v87
	v_cvt_pk_bf16_f32 v121, v91, v95
	v_cvt_pk_bf16_f32 v122, v68, v72
	v_cvt_pk_bf16_f32 v123, v76, v80
	v_cvt_pk_bf16_f32 v124, v84, v88
	v_cvt_pk_bf16_f32 v125, v92, v96
	v_cvt_pk_bf16_f32 v126, v69, v73
	v_cvt_pk_bf16_f32 v127, v77, v81
	v_cvt_pk_bf16_f32 v128, v85, v89
	v_cvt_pk_bf16_f32 v129, v93, v97
	global_store_dwordx4 v112, v[114:117], vcc sc1
	v_add_u32_e32 v112, 0x1000, v112
	global_store_dwordx4 v112, v[118:121], vcc sc1
	v_add_u32_e32 v112, 0x1000, v112
	global_store_dwordx4 v112, v[122:125], vcc sc1
	v_add_u32_e32 v112, 0x1000, v112
	global_store_dwordx4 v112, v[126:129], vcc sc1

; __device__ __forceinline__ unsigned cvt_pk_bf16(float lo, float hi) { unsigned r; asm volatile("v_cvt_pk_bf16_f32 %0, %1, %2" : "=v"(r) : "v"(lo), "v"(hi)); return r; }
; __device__ __forceinline__ void st16_wt(void* p, u32x4 v) { asm volatile("global_store_dwordx4 %0, %1, off sc1\n\ts_nop 1" :: "v"(p), "v"(v) : "memory"); }
; #define SEAM(k) do { if (IN(k) && IN((k) + 1)) { if (hi > 4096) cg::this_grid().sync(); else xcd_barrier(bar); } } while (0)
; __device__ __forceinline__ void tr_item(const float* __restrict__ W, int K, int N, bf16_t* WT, const float* __restrict__ kscale, int rowmode, int item, int lane) {
;     const int nblk = N >> 5, kb = item / nblk, nb = item - kb * nblk;
;     const int c = lane >> 3, q = lane & 7, k0 = kb * 64 + c * 8, n0 = nb * 32 + q * 4;
;     f32x4 v[8];
; #pragma unroll
;     for (int i = 0; i < 8; ++i) v[i] = __builtin_nontemporal_load((const f32x4*)(W + (size_t)(k0 + i) * N + n0));
;     if (kscale) { const f32x4 s0 = *(const f32x4*)(kscale + k0), s1 = *(const f32x4*)(kscale + k0 + 4);
; #pragma unroll
;         for (int i = 0; i < 4; ++i) { v[i] = v[i] * s0[i]; v[4 + i] = v[4 + i] * s1[i]; } }
;     int drow;
;     if (rowmode == 0) drow = n0;
;     else if (rowmode == 3) { const int g = n0 - pg8::C_GA; drow = g < 0 ? n0 : pg8::C_GA + (((g & 2047) >> 7) << 8) + ((g >> 11) << 7) + (g & 127); }
;     else drow = ((n0 >> 7) << 8) + (n0 & 127) + (rowmode == 2 ? 128 : 0);
; #pragma unroll
;     for (int e = 0; e < 4; ++e) { u32x4 o; o.x = cvt_pk_bf16(v[0][e], v[1][e]); o.y = cvt_pk_bf16(v[2][e], v[3][e]); o.z = cvt_pk_bf16(v[4][e], v[5][e]); o.w = cvt_pk_bf16(v[6][e], v[7][e]);
;         pg8::st16_wt(WT + (size_t)(drow + e) * K + k0, o); }
; __global__ void __launch_bounds__(NTHREADS, 2) mk_fwd(Args args) {
;     ...
;         SEAM(pb + 3);
.LBB0_632:
	s_or_b64 exec, exec, s[0:1]
	s_cmpk_lg_u32 s3, 0x100
	s_cbranch_scc1 .Lcv_skip_4
	v_readfirstlane_b32 vcc_lo, v204
	s_nop 3
	s_lshr_b32 vcc_lo, vcc_lo, 6
	s_cmp_eq_u32 vcc_lo, 0
	s_cbranch_scc1 .Lcv_skip_4
	s_cmp_lg_u32 s64, 0
	s_cbranch_scc1 .Lcv_pfwait_4
	v_and_b32_e32 v106, 63, v204
	v_lshrrev_b32_e32 v107, 3, v106
	v_and_b32_e32 v108, 7, v106
	v_readfirstlane_b32 vcc_lo, v204
	s_nop 3
	s_lshr_b32 vcc_lo, vcc_lo, 6
	s_mul_i32 vcc_hi, s85, 7
	s_add_i32 vcc_lo, vcc_lo, vcc_hi
	s_add_i32 vcc_lo, vcc_lo, -1
	s_cmp_ge_u32 vcc_lo, 1664
	s_cbranch_scc1 .Lcv_pfwait_4
	s_add_i32 vcc_lo, vcc_lo, 5376
	s_sub_u32 vcc_lo, vcc_lo, 3520
	v_mov_b32_e32 v113, vcc_lo
	v_mul_u32_u24_e32 v109, 0x5d18, v113
	v_lshrrev_b32_e32 v109, 22, v109
	v_mul_u32_u24_e32 v110, 0xb0, v109
	v_sub_u32_e32 v110, v113, v110
	v_lshlrev_b32_e32 v109, 6, v109
	v_lshl_add_u32 v109, v107, 3, v109
	v_lshlrev_b32_e32 v110, 5, v110
	v_lshl_add_u32 v110, v108, 2, v110
	v_mul_u32_u24_e32 v111, 0x5800, v109
	v_lshl_add_u32 v111, v110, 2, v111
	v_add_u32_e32 v111, 0x2c00000, v111
	v_lshrrev_b32_e32 v112, 7, v110
	v_lshlrev_b32_e32 v112, 8, v112
	v_and_b32_e32 v113, 0x7f, v110
	v_add_u32_e32 v112, v112, v113
	v_lshlrev_b32_e32 v112, 12, v112
	v_lshl_add_u32 v112, v109, 1, v112
	v_lshlrev_b32_e32 v113, 2, v109
	v_add_u32_e32 v113, 0x2000, v113
	v_readlane_b32 vcc_lo, v250, 28
	v_readlane_b32 vcc_hi, v250, 29
	s_nop 4
	global_load_dwordx4 v[98:101], v113, vcc
	global_load_dwordx4 v[102:105], v113, vcc offset:16
	v_readlane_b32 vcc_lo, v250, 30
	v_readlane_b32 vcc_hi, v250, 31
	s_nop 4
	global_load_dwordx4 v[66:69], v111, vcc nt
	v_add_u32_e32 v111, 0x5800, v111
	global_load_dwordx4 v[70:73], v111, vcc nt
	v_add_u32_e32 v111, 0x5800, v111
	global_load_dwordx4 v[74:77], v111, vcc nt
	v_add_u32_e32 v111, 0x5800, v111
	global_load_dwordx4 v[78:81], v111, vcc nt
	v_add_u32_e32 v111, 0x5800, v111
	global_load_dwordx4 v[82:85], v111, vcc nt
	v_add_u32_e32 v111, 0x5800, v111
	global_load_dwordx4 v[86:89], v111, vcc nt
	v_add_u32_e32 v111, 0x5800, v111
	global_load_dwordx4 v[90:93], v111, vcc nt
	v_add_u32_e32 v111, 0x5800, v111
	global_load_dwordx4 v[94:97], v111, vcc nt
	v_readlane_b32 vcc_lo, v250, 36
	v_readlane_b32 vcc_hi, v250, 37
	s_nop 3
	s_add_u32 vcc_lo, vcc_lo, 0x89c0000
	s_addc_u32 vcc_hi, vcc_hi, 0
	s_waitcnt vmcnt(0)
	v_mul_f32_e32 v66, v66, v98
	v_mul_f32_e32 v67, v67, v98
	v_mul_f32_e32 v68, v68, v98
	v_mul_f32_e32 v69, v69, v98
	v_mul_f32_e32 v70, v70, v99
	v_mul_f32_e32 v71, v71, v99
	v_mul_f32_e32 v72, v72, v99
	v_mul_f32_e32 v73, v73, v99
	v_mul_f32_e32 v74, v74, v100
	v_mul_f32_e32 v75, v75, v100
	v_mul_f32_e32 v76, v76, v100
	v_mul_f32_e32 v77, v77, v100
	v_mul_f32_e32 v78, v78, v101
	v_mul_f32_e32 v79, v79, v101
	v_mul_f32_e32 v80, v80, v101
	v_mul_f32_e32 v81, v81, v101
	v_mul_f32_e32 v82, v82, v102
	v_mul_f32_e32 v83, v83, v102
	v_mul_f32_e32 v84, v84, v102
	v_mul_f32_e32 v85, v85, v102
	v_mul_f32_e32 v86, v86, v103
	v_mul_f32_e32 v87, v87, v103
	v_mul_f32_e32 v88, v88, v103
	v_mul_f32_e32 v89, v89, v103
	v_mul_f32_e32 v90, v90, v104
	v_mul_f32_e32 v91, v91, v104
	v_mul_f32_e32 v92, v92, v104
	v_mul_f32_e32 v93, v93, v104
	v_mul_f32_e32 v94, v94, v105
	v_mul_f32_e32 v95, v95, v105
	v_mul_f32_e32 v96, v96, v105
	v_mul_f32_e32 v97, v97, v105
	v_cvt_pk_bf16_f32 v114, v66, v70
	v_cvt_pk_bf16_f32 v115, v74, v78
	v_cvt_pk_bf16_f32 v116, v82, v86
	v_cvt_pk_bf16_f32 v117, v90, v94
	v_cvt_pk_bf16_f32 v118, v67, v71
	v_cvt_pk_bf16_f32 v119, v75, v79
	v_cvt_pk_bf16_f32 v120, v83, v87
	v_cvt_pk_bf16_f32 v121, v91, v95
	v_cvt_pk_bf16_f32 v122, v68, v72
	v_cvt_pk_bf16_f32 v123, v76, v80
	v_cvt_pk_bf16_f32 v124, v84, v88
	v_cvt_pk_bf16_f32 v125, v92, v96
	v_cvt_pk_bf16_f32 v126, v69, v73
	v_cvt_pk_bf16_f32 v127, v77, v81
	v_cvt_pk_bf16_f32 v128, v85, v89
	v_cvt_pk_bf16_f32 v129, v93, v97
	global_store_dwordx4 v112, v[114:117], vcc sc1
	v_add_u32_e32 v112, 0x1000, v112
	global_store_dwordx4 v112, v[118:121], vcc sc1
	v_add_u32_e32 v112, 0x1000, v112
	global_store_dwordx4 v112, v[122:125], vcc sc1
	v_add_u32_e32 v112, 0x1000, v112
	global_store_dwordx4 v112, v[126:129], vcc sc1

; #define SEAM(k) do { if (IN(k) && IN((k) + 1)) { if (hi > 4096) cg::this_grid().sync(); else xcd_barrier(bar); } } while (0)
; __global__ void __launch_bounds__(NTHREADS, 2) mk_fwd(Args args) {
;     ...
;             { int thr = S.nwg - ((S.nwg + G - 1) / G - 1) * G; if (thr >= G) thr = 0;
;                 if (blk >= thr) p0_prologue(args, (blk - thr) * NWAVES + wave, (G - thr) * NWAVES, lane, l == 0 ? 0x07C0u : 0x2000u, false); }
;         }
;         SEAM(pb + 4);
.LBB0_770:
	s_or_b64 exec, exec, s[0:1]
	s_cmpk_lg_u32 s3, 0x100
	s_cbranch_scc1 .Lcv_skip_5
	v_readfirstlane_b32 vcc_lo, v204
	s_nop 3
	s_lshr_b32 vcc_lo, vcc_lo, 6
	s_cmp_eq_u32 vcc_lo, 0
	s_cbranch_scc1 .Lcv_skip_5
.Lcv_pfwait_5:
	s_waitcnt vmcnt(0)

; #define SEAM(k) do { if (IN(k) && IN((k) + 1)) { if (hi > 4096) cg::this_grid().sync(); else xcd_barrier(bar); } } while (0)
; __global__ void __launch_bounds__(NTHREADS, 2) mk_fwd(Args args) {
;     ...
;         SEAM(pb + 5);
.LBB0_961:
	s_or_b64 exec, exec, s[0:1]
	s_cmpk_lg_u32 s3, 0x100
	s_cbranch_scc1 .Lcv_skip_6
	v_readfirstlane_b32 vcc_lo, v204
	s_nop 3
	s_lshr_b32 vcc_lo, vcc_lo, 6
	s_cmp_eq_u32 vcc_lo, 0
	s_cbranch_scc1 .Lcv_skip_6
	s_cmp_lg_u32 s64, 0
	s_cbranch_scc1 .Lcv_skip_6
.Lcv_pfwait_6:
	s_waitcnt vmcnt(0)
